# baseline (speedup 1.0000x reference)
; __device__ __forceinline__ unsigned xb_ld(unsigned* p)              { return __hip_atomic_load(p, __ATOMIC_RELAXED, __HIP_MEMORY_SCOPE_AGENT); }
; __device__ __forceinline__ unsigned xb_add(unsigned* p, unsigned v) { return __hip_atomic_fetch_add(p, v, __ATOMIC_RELAXED, __HIP_MEMORY_SCOPE_AGENT); }
; #define XB_SPIN(cond, bar) do { unsigned _sp = 0; while (cond) { __builtin_amdgcn_s_sleep(1); \
;     if ((++_sp & 255u) == 0u) { if (xb_ld(&(bar)[XB_TMO])) break; if (_sp > XB_SPIN_CAP) { atomicAdd(&(bar)[XB_TMO], 1u); break; } } } } while (0)
; __device__ __forceinline__ void xcd_barrier(unsigned* bar, volatile LAS unsigned* st) {
;     ...
;         const unsigned old = xb_add(&bar[XB_XSUB(x)], 1u);
;         const unsigned gen = old / nloc;
;         if (old + 1u == (gen + 1u) * nloc) {
;             __builtin_amdgcn_fence(__ATOMIC_RELEASE, "agent");
;             asm volatile("s_waitcnt vmcnt(0)" ::: "memory");
;             const unsigned og = xb_add(&bar[XB_TOP], 1u);
;             const unsigned tg = og / nx;
;             if (og + 1u == (tg + 1u) * nx) xb_add(&bar[XB_TOPGEN], 1u);
;             else XB_SPIN(xb_ld(&bar[XB_TOPGEN]) == tg, bar);
;             xb_add(&bar[XB_XGEN(x)], 1u);
;             __builtin_amdgcn_fence(__ATOMIC_ACQUIRE, "agent");
;             asm volatile("s_waitcnt vmcnt(0)" ::: "memory");
.LBB0_534:
	s_andn2_saveexec_b64 s[12:13], s[16:17]
	s_cbranch_execz .LBB0_554
	s_mov_b64 s[12:13], exec
	s_waitcnt lgkmcnt(0)
	s_cmp_lg_u32 s82, 4
	s_cselect_b32 s99, s98, 0
	s_cmp_lg_u32 s99, 0
	s_cbranch_scc1 .Lxl_skip_ple
	buffer_wbl2 sc1
	s_waitcnt vmcnt(0)
	v_mbcnt_lo_u32_b32 v0, s12, 0
	v_mbcnt_hi_u32_b32 v0, s13, v0
	v_cmp_eq_u32_e32 vcc, 0, v0
	s_and_saveexec_b64 s[16:17], vcc
	s_cbranch_execz .LBB0_537
	s_bcnt1_i32_b64 s12, s[12:13]
	v_mov_b32_e32 v3, s12
	v_mov_b32_e32 v4, 0x12b93000
	global_atomic_add v3, v4, v3, s[8:9] offset:1024 sc0

; #define PG8_STAGE(bufoff, gbase, voff) do { _Pragma("unroll") for (int _i = 0; _i < 2; ++_i) \
;         __builtin_amdgcn_global_load_lds((const unsigned*)((const char*)(gbase) + (voff)[_i]), (LAS unsigned*)(lds + (bufoff) + ldsw + _i * 8192), 16, 0, 0); } while (0)
; template <class Epi, class Pre, bool AG = false>
; __device__ __forceinline__ void gemm_phase(LAS unsigned char* lds, const Gemm g, const StaticOrder& S, const Epi& E, const Pre& P) {
;     int tid_ = threadIdx.x; asm volatile("" : "+v"(tid_));
;     const int tid = tid_, wid = __builtin_amdgcn_readfirstlane(tid >> 6), lane = tid & 63, wr = wid >> 2, wc = wid & 3, fr = lane & 15, fq = lane >> 4;
;     const int K = g.K, nt = K / BK;
;     unsigned voffA[2], voffB[2];
; #pragma unroll
;     for (int i = 0; i < 2; ++i) { int R, C; stage_rc(tid * 16 + i * 8192, R, C); const int Rb = Epi::PERM ? ((R & ~31) + perm32(R & 31)) : R;
;         voffA[i] = AG ? (unsigned)((C >> 4) * g.M * 16 + R * 16 + (C & 15)) * 2u : (unsigned)(R * K + C) * 2u; voffB[i] = (unsigned)(Rb * K + C) * 2u; }
;     const size_t kstep = (size_t)(BK * 2), kstepA = AG ? (size_t)(BK / 16) * g.M * 32 : kstep;
;     const size_t hstep = (size_t)HALF * K * 2, hstepA = AG ? (size_t)HALF * 32 : hstep;
;     const size_t tstep = 2 * hstep, tstepA = 2 * hstepA;
;     const unsigned ldsw = (unsigned)wid * 1024u;
;     const int aoff = lds_byte(wr * 64 + fr, fq * 8), boff = lds_byte(wc * 32 + fr, fq * 8);
;     ...
;     Unit cur, nxt; int ui = 0;
;     if (!S.next(0, cur)) return;
;     f32x4 acc[2][2][4][2];
; #pragma unroll
;     for (int a = 0; a < 2; ++a)
; #pragma unroll
;         for (int b = 0; b < 2; ++b)
; #pragma unroll
;             for (int m = 0; m < 4; ++m)
; #pragma unroll
;                 for (int n = 0; n < 2; ++n) acc[a][b][m][n] = (f32x4){0.f, 0.f, 0.f, 0.f};
;     bf16x8 At[4][2], B0[2][2], B1[2][2];
;     const char* cA = (const char*)g.A + (size_t)cur.pm * tstepA; const char* cB = (const char*)g.Bt + (size_t)cur.pn * tstep;
;     PG8_STAGE(PG8_SB(0, 0), cB, voffB); PG8_STAGE(PG8_SB(0, 1), cB + hstep, voffB); PG8_STAGE(PG8_SA(0, 0), cA, voffA); PG8_STAGE(PG8_SA(0, 1), cA + hstepA, voffA);
;     P(S);
.LBB0_555:
	s_and_b64 vcc, exec, s[0:1]
	s_cbranch_vccz .LBB0_196
	v_readlane_b32 s8, v254, 33
	s_mov_b64 s[0:1], s[40:41]
	v_mov_b32_e32 v14, v234
	v_readlane_b32 s9, v254, 34
	s_andn2_b64 vcc, exec, s[8:9]
	v_readfirstlane_b32 s26, v14
	s_cbranch_vccnz .LBB0_586
	v_lshlrev_b32_e32 v0, 4, v14
	v_add_u32_e32 v2, 0x2000, v0
	v_ashrrev_i32_e32 v3, 31, v2
	v_lshrrev_b32_e32 v3, 22, v3
	v_add_u32_e32 v3, v2, v3
	v_ashrrev_i32_e32 v10, 10, v3
	v_mul_i32_i24_e32 v3, 0x400, v10
	v_sub_u32_e32 v2, v2, v3
	v_lshrrev_b32_e32 v3, 4, v2
	v_bitop3_b32 v2, v3, v2, 32 bitop3:0x6c
	v_ashrrev_i32_e32 v3, 31, v2
	v_lshrrev_b32_e32 v3, 26, v3
	v_add_u32_e32 v3, v2, v3
	v_lshlrev_b32_e32 v4, 3, v10
	v_ashrrev_i32_e32 v11, 6, v3
	v_and_b32_e32 v4, -16, v4
	v_add_u32_e32 v4, v11, v4
	v_and_b32_e32 v5, 3, v11
	s_mov_b32 s8, 0x1fffe0
	v_lshrrev_b32_e32 v6, 2, v4
	v_lshlrev_b32_e32 v7, 1, v4
	v_and_b32_e32 v3, 0xc0, v3
	v_and_or_b32 v5, v4, s8, v5
	v_and_b32_e32 v6, 4, v6
	v_and_b32_e32 v7, 24, v7
	v_sub_u32_e32 v2, v2, v3
	v_mov_b32_e32 v8, 1
	v_or3_b32 v5, v5, v6, v7
	v_lshlrev_b32_e32 v6, 5, v10
	v_ashrrev_i16_sdwa v2, v8, sext(v2) dst_sel:DWORD dst_unused:UNUSED_PAD src0_sel:DWORD src1_sel:BYTE_0
	v_and_b32_e32 v6, 32, v6
	v_bfe_i32 v12, v2, 0, 16
	v_add_lshl_u32 v2, v6, v12, 1
	v_lshl_add_u32 v130, v5, 11, v2
	v_lshl_add_u32 v132, v4, 11, v2
	v_bfe_i32 v2, v14, 27, 1
	s_load_dwordx2 s[10:11], s[0:1], 0x100
	v_lshrrev_b32_e32 v2, 22, v2
	v_add_u32_e32 v2, v0, v2
	v_and_b32_e32 v2, 0xfffffc00, v2
	v_sub_u32_e32 v0, v0, v2
	v_readlane_b32 s0, v254, 20
	v_lshrrev_b32_e32 v2, 4, v0
	v_ashrrev_i32_e32 v4, 31, v14
	s_waitcnt lgkmcnt(0)
	s_add_u32 s0, s10, s0
	v_readlane_b32 s1, v254, 22
	v_bitop3_b32 v2, v2, v0, 32 bitop3:0x6c
	v_lshrrev_b32_e32 v4, 26, v4
	s_addc_u32 s1, s11, s1
	v_ashrrev_i32_e32 v0, 31, v2
	v_add_u32_e32 v4, v14, v4
	s_add_u32 s20, s10, 0xc910000
	v_lshrrev_b32_e32 v0, 26, v0
	v_ashrrev_i32_e32 v13, 6, v4
	s_addc_u32 s24, s11, 0
	v_add_u32_e32 v3, v2, v0
	v_lshlrev_b32_e32 v4, 3, v13
	s_add_u32 s25, s0, 0x1080000
	v_ashrrev_i32_e32 v0, 6, v3
	v_and_b32_e32 v4, -16, v4
	s_addc_u32 s30, s1, 0
	v_add_u32_e32 v4, v0, v4
	s_add_u32 s0, s10, 0x12a10000
	v_and_b32_e32 v5, 3, v0
	v_lshrrev_b32_e32 v6, 2, v4
	v_lshlrev_b32_e32 v7, 1, v4
	v_and_b32_e32 v3, 0xc0, v3
	s_addc_u32 s1, s11, 0
	s_ashr_i32 s27, s26, 6
	v_and_or_b32 v5, v4, s8, v5
	v_and_b32_e32 v6, 4, v6
	v_and_b32_e32 v7, 24, v7
	v_sub_u32_e32 v2, v2, v3
	s_lshl_b32 s31, s27, 10
	v_or3_b32 v5, v5, v6, v7
	v_lshlrev_b32_e32 v6, 5, v13
	v_ashrrev_i16_sdwa v2, v8, sext(v2) dst_sel:DWORD dst_unused:UNUSED_PAD src0_sel:DWORD src1_sel:BYTE_0
	v_readlane_b32 s8, v254, 51
	v_and_b32_e32 v6, 32, v6
	v_bfe_i32 v15, v2, 0, 16
	v_readlane_b32 s9, v254, 52
	s_add_u32 s54, s25, s8
	v_add_lshl_u32 v2, v6, v15, 1
	s_addc_u32 s55, s30, s9
	s_add_i32 s38, s31, 0
	v_lshl_add_u32 v134, v5, 11, v2
	s_add_i32 m0, s38, 0x10000
	v_lshl_add_u32 v136, v4, 11, v2
	global_load_lds_dwordx4 v134, s[54:55]
	s_add_i32 m0, s38, 0x12000
	s_add_u32 s8, s54, 0x40000
	global_load_lds_dwordx4 v130, s[54:55]
	s_addc_u32 s9, s55, 0
	s_add_i32 m0, s38, 0x14000
	v_mov_b32_e32 v135, v1
	global_load_lds_dwordx4 v134, s[8:9]
	s_add_i32 m0, s38, 0x16000
	v_mov_b32_e32 v131, v1
	global_load_lds_dwordx4 v130, s[8:9]
	v_readlane_b32 s8, v254, 49
	v_readlane_b32 s9, v254, 50
	s_add_u32 s46, s20, s8
	s_addc_u32 s47, s24, s9
	s_add_i32 s48, s38, 0x2000
	s_mov_b32 m0, s38
	s_add_u32 s8, s46, 0x40000
	global_load_lds_dwordx4 v136, s[46:47]
	s_mov_b32 m0, s48
	s_addc_u32 s9, s47, 0
	s_add_i32 s49, s38, 0x4000
	global_load_lds_dwordx4 v132, s[46:47]
	s_mov_b32 m0, s49
	s_add_i32 s53, s38, 0x6000
	global_load_lds_dwordx4 v136, s[8:9]
	s_mov_b32 m0, s53
	v_mov_b32_e32 v137, v1
	global_load_lds_dwordx4 v132, s[8:9]
	v_mov_b32_e32 v133, v1
	v_mov_b32_e32 v16, v234
	s_movk_i32 s8, 0x100
	v_readlane_b32 s12, v254, 12
	v_lshl_add_u64 v[8:9], s[54:55], 0, v[134:135]
	v_lshl_add_u64 v[6:7], s[54:55], 0, v[130:131]
	v_lshl_add_u64 v[4:5], s[46:47], 0, v[136:137]
	v_lshl_add_u64 v[2:3], s[46:47], 0, v[132:133]
	s_movk_i32 s28, 0xc400
	v_cmp_gt_i32_e64 s[8:9], s8, v16
	v_lshl_add_u32 v17, v16, 2, s12
	s_mov_b64 s[16:17], s[2:3]
	s_cmp_eq_u32 s18, 0x100
	s_cbranch_scc1 .Lpr_win_begin
	s_branch .LBB0_560

; #define LAS __attribute__((address_space(3)))
; template <int NS> __device__ __forceinline__ void prep_rstd(LAS unsigned char* lds, const float* part, const pg8::StaticOrder& S, float inv_n) {
;     LAS float* t = (LAS float*)(lds + LDS_RS_OFF);
;     int tid = threadIdx.x; asm volatile("" : "+v"(tid));
;     pg8::Unit u;
;     for (int i = 0; i < RS_MAX_UNITS && S.next(i, u); ++i) {
;         if (tid < 256) {
;             const f32x4* p = (const f32x4*)(part + (size_t)(u.pm * 256 + tid) * NS);
;             f32x4 a = p[0], b = p[1];
;             float s = ((a.x + a.y) + (a.z + a.w)) + ((b.x + b.y) + (b.z + b.w));
;             if (NS == 16) { a = p[2]; b = p[3]; s += ((a.x + a.y) + (a.z + a.w)) + ((b.x + b.y) + (b.z + b.w)); }
;             t[i * 256 + tid] = rsqrtf(s * inv_n + EPS);
;         }
;     }
;     __syncthreads();
.Lpr_win_begin:
	s_and_saveexec_b64 s[12:13], s[8:9]
	s_cbranch_execz .Lpr_win_done
	v_lshlrev_b32_e32 v116, 6, v16
	s_mov_b32 s28, 0
	s_mov_b32 s16, s2
	s_cmp_gt_u32 s16, 0x1ff
	s_cbranch_scc1 .Lpr_win_wait
	s_and_b32 s29, s16, 7
	s_lshl_b32 s29, s29, 6
	s_lshr_b32 s42, s16, 3
	s_add_i32 s29, s29, s42
	s_lshr_b32 s42, s29, 5
	s_lshl_b32 s42, s42, 2
	s_and_b32 s29, s29, 3
	s_or_b32 s29, s29, s42
	s_lshl_b32 s29, s29, 14
	s_add_u32 s42, s0, s29
	s_addc_u32 s43, s1, 0
	global_load_dwordx4 v[18:21], v116, s[42:43]
	global_load_dwordx4 v[22:25], v116, s[42:43] offset:16
	global_load_dwordx4 v[26:29], v116, s[42:43] offset:32
	global_load_dwordx4 v[30:33], v116, s[42:43] offset:48
	s_add_i32 s28, s28, 1
	s_add_i32 s16, s16, s18
	s_cmp_gt_u32 s16, 0x1ff
	s_cbranch_scc1 .Lpr_win_wait
	s_and_b32 s29, s16, 7
	s_lshl_b32 s29, s29, 6
	s_lshr_b32 s42, s16, 3
	s_add_i32 s29, s29, s42
	s_lshr_b32 s42, s29, 5
	s_lshl_b32 s42, s42, 2
	s_and_b32 s29, s29, 3
	s_or_b32 s29, s29, s42
	s_lshl_b32 s29, s29, 14
	s_add_u32 s42, s0, s29
	s_addc_u32 s43, s1, 0
	global_load_dwordx4 v[36:39], v116, s[42:43]
	global_load_dwordx4 v[40:43], v116, s[42:43] offset:16
	global_load_dwordx4 v[44:47], v116, s[42:43] offset:32
	global_load_dwordx4 v[48:51], v116, s[42:43] offset:48
	s_add_i32 s28, s28, 1
	s_add_i32 s16, s16, s18
.Lpr_win_wait:
	s_waitcnt vmcnt(0)
	s_cmp_lt_u32 s28, 1
	s_cbranch_scc1 .Lpr_win_done
	v_add_f32_e32 v18, v18, v19
	v_add_f32_e32 v20, v20, v21
	v_add_f32_e32 v18, v18, v20
	v_add_f32_e32 v22, v22, v23
	v_add_f32_e32 v24, v24, v25
	v_add_f32_e32 v22, v22, v24
	v_add_f32_e32 v26, v26, v27
	v_add_f32_e32 v28, v28, v29
	v_add_f32_e32 v26, v26, v28
	v_add_f32_e32 v30, v30, v31
	v_add_f32_e32 v32, v32, v33
	v_add_f32_e32 v30, v30, v32
	v_add_f32_e32 v18, v18, v22
	v_add_f32_e32 v26, v26, v30
	v_add_f32_e32 v118, v18, v26
	v_fmamk_f32 v118, v118, 0x3a800000, v230
	v_mul_f32_e32 v124, 0x4b800000, v118
	v_cmp_gt_f32_e32 vcc, s35, v118
	s_nop 1
	v_cndmask_b32_e32 v118, v118, v124, vcc
	v_rsq_f32_e32 v118, v118
	s_nop 0
	v_mul_f32_e32 v124, 0x45800000, v118
	v_cndmask_b32_e32 v118, v118, v124, vcc
	ds_write_b32 v17, v118
	s_cmp_lt_u32 s28, 2
	s_cbranch_scc1 .Lpr_win_done
	v_add_f32_e32 v36, v36, v37
	v_add_f32_e32 v38, v38, v39
	v_add_f32_e32 v36, v36, v38
	v_add_f32_e32 v40, v40, v41
	v_add_f32_e32 v42, v42, v43
	v_add_f32_e32 v40, v40, v42
	v_add_f32_e32 v44, v44, v45
	v_add_f32_e32 v46, v46, v47
	v_add_f32_e32 v44, v44, v46
	v_add_f32_e32 v48, v48, v49
	v_add_f32_e32 v50, v50, v51
	v_add_f32_e32 v48, v48, v50
	v_add_f32_e32 v36, v36, v40
	v_add_f32_e32 v44, v44, v48
	v_add_f32_e32 v119, v36, v44
	v_fmamk_f32 v119, v119, 0x3a800000, v230
	v_mul_f32_e32 v125, 0x4b800000, v119
	v_cmp_gt_f32_e32 vcc, s35, v119
	s_nop 1
	v_cndmask_b32_e32 v119, v119, v125, vcc
	v_rsq_f32_e32 v119, v119
	s_nop 0
	v_mul_f32_e32 v125, 0x45800000, v119
	v_cndmask_b32_e32 v119, v119, v125, vcc
	ds_write_b32 v17, v119 offset:1024
.Lpr_win_done:
	s_or_b64 exec, exec, s[12:13]
.LBB0_567:
	s_ashr_i32 s8, s26, 8
	s_cmp_eq_u32 s8, 1
	s_cselect_b64 s[0:1], -1, 0
	s_cmp_lg_u32 s8, 1
	s_waitcnt vmcnt(0) lgkmcnt(0)
	s_barrier
	s_cbranch_scc1 .LBB0_569
	s_barrier
